# P2 attention NOMAX loop: row-sum chain of 33 v_add_f32 per K-tile replaced by 15 v_pk_add_f32 + 1 v_add_f32 (VALU op-count reduction), on top of P1 LDS tables
# baseline (speedup 1.0000x reference)
.LBB0_1097:
	s_mov_b32 s7, s89
	v_mov_b64_e32 v[226:227], v[100:101]
	s_mov_b32 s88, s38
	v_mov_b64_e32 v[228:229], v[98:99]
	s_mov_b32 s37, s87
	v_add_u32_e32 v198, s36, v233
	ds_read_b64_tr_b16 v[200:201], v198 offset:24576
	ds_read_b64_tr_b16 v[202:203], v198 offset:25088
	v_pk_add_f32 v[98:99], v[82:83], v[84:85]
	v_pk_add_f32 v[98:99], v[86:87], v[98:99]
	v_cvt_pk_bf16_f32 v158, v82, v83
	v_cvt_pk_bf16_f32 v159, v84, v85
	s_waitcnt lgkmcnt(9)
	v_mfma_f32_32x32x16_bf16 v[114:129], v[190:193], v[130:133], v[50:65]
	ds_read_b64_tr_b16 v[82:83], v198 offset:28672
	ds_read_b64_tr_b16 v[84:85], v198 offset:29184
	v_pk_add_f32 v[98:99], v[88:89], v[98:99]
	v_pk_add_f32 v[146:147], v[90:91], v[98:99]
	s_waitcnt lgkmcnt(10)
	v_mfma_f32_32x32x16_bf16 v[98:113], v[186:189], v[130:133], v[50:65]
	v_cvt_pk_bf16_f32 v160, v86, v87
	v_cvt_pk_bf16_f32 v161, v88, v89
	ds_read_b64_tr_b16 v[86:87], v198 offset:25600
	ds_read_b64_tr_b16 v[88:89], v198 offset:26112
	v_pk_add_f32 v[146:147], v[92:93], v[146:147]
	v_pk_add_f32 v[146:147], v[94:95], v[146:147]
	v_cvt_pk_bf16_f32 v154, v90, v91
	v_cvt_pk_bf16_f32 v155, v92, v93
	s_waitcnt lgkmcnt(11)
	v_mfma_f32_32x32x16_bf16 v[114:129], v[182:185], v[134:137], v[114:129]
	ds_read_b64_tr_b16 v[90:91], v198 offset:29696
	ds_read_b64_tr_b16 v[92:93], v198 offset:30208
	s_waitcnt lgkmcnt(12)
	v_mfma_f32_32x32x16_bf16 v[98:113], v[178:181], v[134:137], v[98:113]
	v_pk_add_f32 v[146:147], v[96:97], v[146:147]
	v_pk_add_f32 v[146:147], v[66:67], v[146:147]
	v_cvt_pk_bf16_f32 v156, v94, v95
	v_cvt_pk_bf16_f32 v157, v96, v97
	ds_read_b64_tr_b16 v[94:95], v198 offset:26624
	ds_read_b64_tr_b16 v[96:97], v198 offset:27136
	v_pk_add_f32 v[146:147], v[68:69], v[146:147]
	v_pk_add_f32 v[146:147], v[70:71], v[146:147]
	v_cvt_pk_bf16_f32 v150, v66, v67
	v_cvt_pk_bf16_f32 v151, v68, v69
	s_waitcnt lgkmcnt(13)
	v_mfma_f32_32x32x16_bf16 v[114:129], v[174:177], v[138:141], v[114:129]
	ds_read_b64_tr_b16 v[66:67], v198 offset:30720
	ds_read_b64_tr_b16 v[68:69], v198 offset:31232
	s_waitcnt lgkmcnt(14)
	v_mfma_f32_32x32x16_bf16 v[98:113], v[170:173], v[138:141], v[98:113]
	v_pk_add_f32 v[146:147], v[72:73], v[146:147]
	v_pk_add_f32 v[146:147], v[74:75], v[146:147]
	v_cvt_pk_bf16_f32 v152, v70, v71
	v_cvt_pk_bf16_f32 v153, v72, v73
	ds_read_b64_tr_b16 v[70:71], v198 offset:27648
	ds_read_b64_tr_b16 v[72:73], v198 offset:28160
	v_pk_add_f32 v[146:147], v[76:77], v[146:147]
	v_pk_add_f32 v[170:171], v[78:79], v[146:147]
	v_cvt_pk_bf16_f32 v146, v74, v75
	v_cvt_pk_bf16_f32 v147, v76, v77
	s_waitcnt lgkmcnt(14)
	v_mfma_f32_32x32x16_bf16 v[114:129], v[166:169], v[142:145], v[114:129]
	ds_read_b64_tr_b16 v[74:75], v198 offset:31744
	ds_read_b64_tr_b16 v[76:77], v198 offset:32256
	v_mfma_f32_32x32x16_bf16 v[98:113], v[162:165], v[142:145], v[98:113]
	v_pk_add_f32 v[148:149], v[80:81], v[170:171]
	v_add_f32_e32 v198, v148, v149
	v_cvt_pk_bf16_f32 v148, v78, v79
	v_cvt_pk_bf16_f32 v149, v80, v81
	v_lshl_add_u64 v[78:79], v[196:197], 0, s[24:25]
	s_add_i32 s0, s87, s84
	s_mov_b32 s1, m0
	s_mov_b32 m0, s0
	s_nop 0
	global_load_lds_dwordx4 v[78:79], off
	s_mov_b32 m0, s1
	v_lshl_add_u64 v[78:79], v[194:195], 0, s[24:25]
	s_add_i32 s0, s89, s8
	s_mov_b32 s1, m0
	s_mov_b32 m0, s0
	s_nop 0
	global_load_lds_dwordx4 v[78:79], off
	s_mov_b32 m0, s1
	s_waitcnt lgkmcnt(14)
	v_mfma_f32_32x32x16_bf16 v[18:33], v[158:161], v[200:203], v[18:33]
	v_exp_f32_e32 v114, v114
	v_exp_f32_e32 v115, v115
	v_exp_f32_e32 v116, v116
	v_exp_f32_e32 v117, v117
	s_waitcnt lgkmcnt(12)
	v_mfma_f32_32x32x16_bf16 v[34:49], v[158:161], v[82:85], v[34:49]
	v_exp_f32_e32 v118, v118
	v_exp_f32_e32 v119, v119
	v_exp_f32_e32 v120, v120
	v_exp_f32_e32 v121, v121
	v_add_u32_e32 v82, s7, v232
	ds_read_b128 v[78:81], v82
	ds_read_b128 v[162:165], v82 offset:512
	s_waitcnt lgkmcnt(12)
	v_mfma_f32_32x32x16_bf16 v[18:33], v[154:157], v[86:89], v[18:33]
	v_exp_f32_e32 v122, v122
	v_exp_f32_e32 v123, v123
	v_exp_f32_e32 v124, v124
	v_exp_f32_e32 v125, v125
	ds_read_b128 v[166:169], v82 offset:2048
	ds_read_b128 v[170:173], v82 offset:2560
	s_waitcnt lgkmcnt(12)
	v_mfma_f32_32x32x16_bf16 v[34:49], v[154:157], v[90:93], v[34:49]
	v_exp_f32_e32 v126, v126
	v_exp_f32_e32 v127, v127
	v_exp_f32_e32 v128, v128
	v_exp_f32_e32 v129, v129
	ds_read_b128 v[174:177], v82 offset:4096
	ds_read_b128 v[178:181], v82 offset:4608
	s_waitcnt lgkmcnt(12)
	v_mfma_f32_32x32x16_bf16 v[18:33], v[150:153], v[94:97], v[18:33]
	v_exp_f32_e32 v98, v98
	v_exp_f32_e32 v99, v99
	v_exp_f32_e32 v100, v100
	v_exp_f32_e32 v101, v101
	ds_read_b128 v[182:185], v82 offset:6144
	ds_read_b128 v[186:189], v82 offset:6656
	s_waitcnt lgkmcnt(12)
	v_mfma_f32_32x32x16_bf16 v[34:49], v[150:153], v[66:69], v[34:49]
	v_exp_f32_e32 v102, v102
	v_exp_f32_e32 v103, v103
	v_exp_f32_e32 v104, v104
	v_exp_f32_e32 v105, v105
	s_waitcnt lgkmcnt(10)
	v_mfma_f32_32x32x16_bf16 v[18:33], v[146:149], v[70:73], v[18:33]
	v_exp_f32_e32 v106, v106
	v_exp_f32_e32 v107, v107
	v_exp_f32_e32 v108, v108
	v_exp_f32_e32 v109, v109
	s_waitcnt lgkmcnt(8)
	v_mfma_f32_32x32x16_bf16 v[34:49], v[146:149], v[74:77], v[34:49]
	v_exp_f32_e32 v110, v110
	v_exp_f32_e32 v111, v111
	v_exp_f32_e32 v112, v112
	v_exp_f32_e32 v113, v113
	s_waitcnt vmcnt(2) lgkmcnt(0)
	s_barrier
; #define WAIT_BAR(N) asm volatile("s_waitcnt vmcnt(" #N ") lgkmcnt(0)\n\ts_barrier":::"memory")
;   #define RESC() do{ if(resc){ asm volatile("s_waitcnt lgkmcnt(0)":::"memory"); \
;       _Pragma("unroll") for(int d_=0;d_<2;++d_) _Pragma("unroll") for(int r=0;r<16;++r)o[d_][r]*=wsf[crow(r,hi)]; } }while(0)
;   #define ROT() do{sl_prev=sl_cur;sl_cur=sl_next;sl_next=(sl_next==(NSLOT-1)*SLOTB)?0:sl_next+SLOTB;}while(0)
; template<int THRL,bool NOMAX> __device__ __forceinline__ void attn_unit(long rowbase,int NT,int h,int qb,const bf16*Q,const bf16*__restrict__ Kh,const bf16*__restrict__ Vh,bf16*O,char*shm,
;     bool first,bool has_next,long n_rowbase,int n_h,int n_qb,const bf16*__restrict__ n_Kh,bf16x8 (&qr)[4]){
;     ...
;   int t=1;
;     ...
;   for(;t+5<NT;t+=2){
;     STEP(pB0,pB1,pA0,pA1,t,true,true,true);     WAIT_BAR(2); RESC(); ROT();
;     STEP(pA0,pA1,pB0,pB1,t+1,true,true,true);   WAIT_BAR(2); RESC(); ROT();
	s_add_i32 s0, s89, 0x2000
	s_cmpk_lg_i32 s89, 0x4000
	s_cselect_b32 s87, s0, 0
	v_add_u32_e32 v199, s37, v233
	ds_read_b64_tr_b16 v[190:191], v199 offset:24576
	ds_read_b64_tr_b16 v[192:193], v199 offset:25088
	s_waitcnt lgkmcnt(9)
	v_mfma_f32_32x32x16_bf16 v[82:97], v[78:81], v[130:133], v[50:65]
	v_pk_add_f32 v[66:67], v[114:115], v[116:117]
	v_pk_add_f32 v[66:67], v[118:119], v[66:67]
	v_cvt_pk_bf16_f32 v158, v114, v115
	v_cvt_pk_bf16_f32 v159, v116, v117
	ds_read_b64_tr_b16 v[114:115], v199 offset:28672
	ds_read_b64_tr_b16 v[116:117], v199 offset:29184
	v_pk_add_f32 v[66:67], v[120:121], v[66:67]
	v_pk_add_f32 v[146:147], v[122:123], v[66:67]
	s_waitcnt lgkmcnt(10)
	v_mfma_f32_32x32x16_bf16 v[66:81], v[162:165], v[130:133], v[50:65]
	v_cvt_pk_bf16_f32 v160, v118, v119
	v_cvt_pk_bf16_f32 v161, v120, v121
	ds_read_b64_tr_b16 v[118:119], v199 offset:25600
	ds_read_b64_tr_b16 v[120:121], v199 offset:26112
	s_waitcnt lgkmcnt(11)
	v_mfma_f32_32x32x16_bf16 v[82:97], v[166:169], v[134:137], v[82:97]
	v_pk_add_f32 v[146:147], v[124:125], v[146:147]
	v_pk_add_f32 v[146:147], v[126:127], v[146:147]
	v_cvt_pk_bf16_f32 v154, v122, v123
	v_cvt_pk_bf16_f32 v155, v124, v125
	ds_read_b64_tr_b16 v[122:123], v199 offset:29696
	ds_read_b64_tr_b16 v[124:125], v199 offset:30208
	s_waitcnt lgkmcnt(12)
	v_mfma_f32_32x32x16_bf16 v[66:81], v[170:173], v[134:137], v[66:81]
	v_pk_add_f32 v[146:147], v[128:129], v[146:147]
	v_pk_add_f32 v[146:147], v[98:99], v[146:147]
	v_cvt_pk_bf16_f32 v156, v126, v127
	v_cvt_pk_bf16_f32 v157, v128, v129
	ds_read_b64_tr_b16 v[126:127], v199 offset:26624
	ds_read_b64_tr_b16 v[128:129], v199 offset:27136
	s_waitcnt lgkmcnt(13)
	v_mfma_f32_32x32x16_bf16 v[82:97], v[174:177], v[138:141], v[82:97]
	v_pk_add_f32 v[146:147], v[100:101], v[146:147]
	v_pk_add_f32 v[146:147], v[102:103], v[146:147]
	v_cvt_pk_bf16_f32 v150, v98, v99
	v_cvt_pk_bf16_f32 v151, v100, v101
	ds_read_b64_tr_b16 v[98:99], v199 offset:30720
	ds_read_b64_tr_b16 v[100:101], v199 offset:31232
	s_waitcnt lgkmcnt(14)
	v_mfma_f32_32x32x16_bf16 v[66:81], v[178:181], v[138:141], v[66:81]
	v_pk_add_f32 v[146:147], v[104:105], v[146:147]
	v_pk_add_f32 v[146:147], v[106:107], v[146:147]
	v_cvt_pk_bf16_f32 v152, v102, v103
	v_cvt_pk_bf16_f32 v153, v104, v105
	ds_read_b64_tr_b16 v[102:103], v199 offset:27648
	ds_read_b64_tr_b16 v[104:105], v199 offset:28160
	s_waitcnt lgkmcnt(14)
	v_mfma_f32_32x32x16_bf16 v[82:97], v[182:185], v[142:145], v[82:97]
	v_pk_add_f32 v[146:147], v[108:109], v[146:147]
	v_pk_add_f32 v[162:163], v[110:111], v[146:147]
	v_cvt_pk_bf16_f32 v146, v106, v107
	v_cvt_pk_bf16_f32 v147, v108, v109
	ds_read_b64_tr_b16 v[106:107], v199 offset:31744
	ds_read_b64_tr_b16 v[108:109], v199 offset:32256
	v_mfma_f32_32x32x16_bf16 v[66:81], v[186:189], v[142:145], v[66:81]
	v_pk_add_f32 v[148:149], v[112:113], v[162:163]
	v_add_f32_e32 v199, v148, v149
	v_cvt_pk_bf16_f32 v148, v110, v111
	v_cvt_pk_bf16_f32 v149, v112, v113
	s_add_i32 s0, s89, s84
	s_mov_b32 s1, m0
	s_mov_b32 m0, s0
	s_nop 0
	global_load_lds_dwordx4 v[196:197], off
	s_mov_b32 m0, s1
	s_add_i32 s0, s87, s8
	s_mov_b32 s1, m0
	s_mov_b32 m0, s0
	s_nop 0
	global_load_lds_dwordx4 v[194:195], off
	s_mov_b32 m0, s1
	s_waitcnt lgkmcnt(14)
	v_mfma_f32_32x32x16_bf16 v[18:33], v[158:161], v[190:193], v[18:33]
	v_exp_f32_e32 v82, v82
	v_exp_f32_e32 v83, v83
	v_exp_f32_e32 v84, v84
	v_exp_f32_e32 v85, v85
	s_waitcnt lgkmcnt(12)
	v_mfma_f32_32x32x16_bf16 v[34:49], v[158:161], v[114:117], v[34:49]
	v_exp_f32_e32 v86, v86
	v_exp_f32_e32 v87, v87
	v_exp_f32_e32 v88, v88
	v_exp_f32_e32 v89, v89
	v_add_u32_e32 v110, s87, v232
	ds_read_b128 v[190:193], v110
	ds_read_b128 v[186:189], v110 offset:512
	s_waitcnt lgkmcnt(12)
	v_mfma_f32_32x32x16_bf16 v[18:33], v[154:157], v[118:121], v[18:33]
	v_exp_f32_e32 v90, v90
	v_exp_f32_e32 v91, v91
	v_exp_f32_e32 v92, v92
	v_exp_f32_e32 v93, v93
	ds_read_b128 v[182:185], v110 offset:2048
	ds_read_b128 v[178:181], v110 offset:2560
	s_waitcnt lgkmcnt(12)
	v_mfma_f32_32x32x16_bf16 v[34:49], v[154:157], v[122:125], v[34:49]
	v_exp_f32_e32 v94, v94
	v_exp_f32_e32 v95, v95
	v_exp_f32_e32 v96, v96
	v_exp_f32_e32 v97, v97
	ds_read_b128 v[174:177], v110 offset:4096
	ds_read_b128 v[170:173], v110 offset:4608
	s_waitcnt lgkmcnt(12)
	v_mfma_f32_32x32x16_bf16 v[18:33], v[150:153], v[126:129], v[18:33]
	v_exp_f32_e32 v66, v66
	v_exp_f32_e32 v67, v67
	v_exp_f32_e32 v68, v68
	v_exp_f32_e32 v69, v69
	ds_read_b128 v[166:169], v110 offset:6144
	ds_read_b128 v[162:165], v110 offset:6656
	s_waitcnt lgkmcnt(12)
	v_mfma_f32_32x32x16_bf16 v[34:49], v[150:153], v[98:101], v[34:49]
	v_exp_f32_e32 v70, v70
	v_exp_f32_e32 v71, v71
	v_exp_f32_e32 v72, v72
	v_exp_f32_e32 v73, v73
	s_waitcnt lgkmcnt(10)
	v_mfma_f32_32x32x16_bf16 v[18:33], v[146:149], v[102:105], v[18:33]
	v_exp_f32_e32 v74, v74
	v_exp_f32_e32 v75, v75
	v_exp_f32_e32 v76, v76
	v_exp_f32_e32 v77, v77
	s_waitcnt lgkmcnt(8)
	v_mfma_f32_32x32x16_bf16 v[34:49], v[146:149], v[106:109], v[34:49]
	v_exp_f32_e32 v78, v78
	v_exp_f32_e32 v79, v79
	v_exp_f32_e32 v80, v80
	v_exp_f32_e32 v81, v81
	s_add_i32 s0, s87, 0x2000
	s_waitcnt vmcnt(2) lgkmcnt(0)
	s_barrier
	s_cmpk_lg_i32 s87, 0x4000
	v_add_f32_e32 v102, v206, v198
	s_mov_b32 s36, s89
	s_cselect_b32 s89, s0, 0
	s_add_i32 s6, s6, 2
	s_add_i32 s38, s38, 2
	v_lshl_add_u64 v[194:195], v[194:195], 0, s[14:15]
	v_lshl_add_u64 v[196:197], v[196:197], 0, s[14:15]
	v_lshl_add_u64 v[100:101], v[226:227], 0, s[14:15]
	v_lshl_add_u64 v[98:99], v[228:229], 0, s[14:15]
	s_cmp_ge_u32 s6, s82
	v_add_f32_e32 v206, v102, v199
	s_cbranch_scc0 .LBB0_1097
	s_add_i32 s0, s6, -4
	s_cmp_ge_u32 s0, s82
	s_cbranch_scc1 .LBB0_1132
	s_add_i32 s90, s6, -5
